# NSA sliding-window branch: fully-valid tiles also take the hand-written in-place fast path
# speedup vs baseline: 1.0243x; 1.0039x over previous
; template <int MODE> __device__ __forceinline__ void tile_softmax(f32x4 (&S)[4], bool rowv, int kfirst, int klo, unsigned kspan, float& l) {
;     ...
;         for (int j = 0; j < 4; ++j) { float e = __builtin_amdgcn_exp2f(S[st][j]);
;             if (MODE == 1) e = rowv ? e : 0.f;
;             if (MODE == 2) e = ((unsigned)(kfirst + st * 16 + j - klo) <= kspan) ? e : 0.f;
;             S[st][j] = e; ps += e; }
.Lsf_qk_done1:
	s_nop 3
	ds_read_b64 v[132:133], v126 offset:8192
	ds_read_b64 v[134:135], v127 offset:8192
	ds_read_b64 v[148:149], v128 offset:8192
	ds_read_b64 v[150:151], v129 offset:8192
	ds_read_b64 v[136:137], v126 offset:10240
	ds_read_b64 v[138:139], v127 offset:10240
	ds_read_b64 v[152:153], v128 offset:10240
	ds_read_b64 v[154:155], v129 offset:10240
	ds_read_b64 v[140:141], v126 offset:12288
	ds_read_b64 v[142:143], v127 offset:12288
	ds_read_b64 v[116:117], v128 offset:12288
	ds_read_b64 v[118:119], v129 offset:12288
	ds_read_b64 v[144:145], v126 offset:14336
	ds_read_b64 v[146:147], v127 offset:14336
	ds_read_b64 v[120:121], v128 offset:14336
	ds_read_b64 v[122:123], v129 offset:14336
	s_nop 7
	s_and_b64 vcc, exec, s[56:57]
	s_cbranch_vccz .Lsf_sm_done0
	v_exp_f32_e32 v16, v16
	v_exp_f32_e32 v17, v17
	v_exp_f32_e32 v18, v18
	v_exp_f32_e32 v19, v19
	v_exp_f32_e32 v20, v20
	v_exp_f32_e32 v21, v21
	v_exp_f32_e32 v22, v22
	v_exp_f32_e32 v23, v23
	v_exp_f32_e32 v24, v24
	v_exp_f32_e32 v25, v25
	v_exp_f32_e32 v26, v26
	v_exp_f32_e32 v27, v27
	v_exp_f32_e32 v28, v28
	v_exp_f32_e32 v29, v29
	v_exp_f32_e32 v30, v30
	v_exp_f32_e32 v31, v31
	s_cmp_eq_u64 s[98:99], -1
	s_cbranch_scc1 .Lsf_all0
	v_cndmask_b32_e64 v16, 0, v16, s[98:99]
	v_cndmask_b32_e64 v17, 0, v17, s[98:99]
	v_cndmask_b32_e64 v18, 0, v18, s[98:99]
	v_cndmask_b32_e64 v19, 0, v19, s[98:99]
	v_cndmask_b32_e64 v20, 0, v20, s[98:99]
	v_cndmask_b32_e64 v21, 0, v21, s[98:99]
	v_cndmask_b32_e64 v22, 0, v22, s[98:99]
	v_cndmask_b32_e64 v23, 0, v23, s[98:99]
	v_cndmask_b32_e64 v24, 0, v24, s[98:99]
	v_cndmask_b32_e64 v25, 0, v25, s[98:99]
	v_cndmask_b32_e64 v26, 0, v26, s[98:99]
	v_cndmask_b32_e64 v27, 0, v27, s[98:99]
	v_cndmask_b32_e64 v28, 0, v28, s[98:99]
	v_cndmask_b32_e64 v29, 0, v29, s[98:99]
	v_cndmask_b32_e64 v30, 0, v30, s[98:99]
	v_cndmask_b32_e64 v31, 0, v31, s[98:99]

; template <int MODE> __device__ __forceinline__ void tile_softmax(f32x4 (&S)[4], bool rowv, int kfirst, int klo, unsigned kspan, float& l) {
;     ...
;         for (int j = 0; j < 4; ++j) { float e = __builtin_amdgcn_exp2f(S[st][j]);
;             if (MODE == 1) e = rowv ? e : 0.f;
;             if (MODE == 2) e = ((unsigned)(kfirst + st * 16 + j - klo) <= kspan) ? e : 0.f;
;             S[st][j] = e; ps += e; }
.Lsf_sm_done0:
	s_and_b64 vcc, exec, s[28:29]
	s_cbranch_vccz .Lsf_sm_done1
	v_exp_f32_e32 v32, v32
	v_exp_f32_e32 v33, v33
	v_exp_f32_e32 v34, v34
	v_exp_f32_e32 v35, v35
	v_exp_f32_e32 v36, v36
	v_exp_f32_e32 v37, v37
	v_exp_f32_e32 v38, v38
	v_exp_f32_e32 v39, v39
	v_exp_f32_e32 v40, v40
	v_exp_f32_e32 v41, v41
	v_exp_f32_e32 v42, v42
	v_exp_f32_e32 v43, v43
	v_exp_f32_e32 v44, v44
	v_exp_f32_e32 v45, v45
	v_exp_f32_e32 v46, v46
	v_exp_f32_e32 v47, v47
	s_cmp_eq_u64 s[100:101], -1
	s_cbranch_scc1 .Lsf_all1
	v_cndmask_b32_e64 v32, 0, v32, s[100:101]
	v_cndmask_b32_e64 v33, 0, v33, s[100:101]
	v_cndmask_b32_e64 v34, 0, v34, s[100:101]
	v_cndmask_b32_e64 v35, 0, v35, s[100:101]
	v_cndmask_b32_e64 v36, 0, v36, s[100:101]
	v_cndmask_b32_e64 v37, 0, v37, s[100:101]
	v_cndmask_b32_e64 v38, 0, v38, s[100:101]
	v_cndmask_b32_e64 v39, 0, v39, s[100:101]
	v_cndmask_b32_e64 v40, 0, v40, s[100:101]
	v_cndmask_b32_e64 v41, 0, v41, s[100:101]
	v_cndmask_b32_e64 v42, 0, v42, s[100:101]
	v_cndmask_b32_e64 v43, 0, v43, s[100:101]
	v_cndmask_b32_e64 v44, 0, v44, s[100:101]
	v_cndmask_b32_e64 v45, 0, v45, s[100:101]
	v_cndmask_b32_e64 v46, 0, v46, s[100:101]
	v_cndmask_b32_e64 v47, 0, v47, s[100:101]

; __device__ __forceinline__ void nsa_wg_task(bf16_t* zb, const bf16_t* kcb, const bf16_t* vctb, const bf16_t* vst, const bf16_t* vwt, int g, int T0, float* accb, LAS unsigned char* lds, int wave, int lane, int tid) {
;     ...
;             const int s = i - 2 * nc, kb0 = s * 64;
;             bool any[2], mine[2], all4[2];
;             const unsigned mwd0 = wM[ti * 4 + (s >> 5)], mwd1 = wM[(4 + ti) * 4 + (s >> 5)];
;             nsa_loadk(kbuf, offk0, offk1, ka, kb);
; #pragma unroll
;             for (int r = 0; r < 2; ++r) { const unsigned mwd = r == 0 ? mwd0 : mwd1; mine[r] = ((mwd >> (s & 31)) & 1u) != 0u; const unsigned long long bal = __ballot(mine[r]); any[r] = bal != 0ull && kb0 <= tmax[r]; all4[r] = bal == ~0ull; }
;             if (any[0] || any[1]) {
.LBB0_209:
	s_add_i32 s44, s34, s75
	s_cmp_gt_i32 s44, s38
	s_mov_b64 s[20:21], -1
	s_cbranch_scc1 .LBB0_208
	s_add_i32 s2, s34, s1
	s_lshl_b32 s2, s2, 14
	s_add_i32 s45, s2, 0
	s_cmp_ge_i32 s44, s70
	s_cbranch_scc0 .LBB0_334
	s_cmp_ge_i32 s44, s71
	s_cbranch_scc0 .LBB0_260
	s_cmp_gt_i32 s44, s84
	s_cbranch_scc1 .LBB0_240
	s_sub_i32 s2, s44, s71
	s_ashr_i32 s20, s2, 5
	s_waitcnt lgkmcnt(0)
	v_lshl_add_u32 v16, s20, 2, v207
	ds_read2_b32 v[16:17], v16 offset1:16
	s_lshl_b32 s21, 1, s2
	s_lshl_b32 s20, s2, 6
	v_mov_b64_e32 v[32:33], v[84:85]
	v_mov_b64_e32 v[36:37], v[88:89]
	s_waitcnt lgkmcnt(0)
	v_and_b32_e32 v16, s21, v16
	v_cmp_ne_u32_e64 s[24:25], 0, v16
	s_cmp_lg_u64 s[24:25], 0
	s_cselect_b64 s[22:23], -1, 0
	s_cmp_le_i32 s20, s85
	v_and_b32_e32 v17, s21, v17
	s_cselect_b64 s[28:29], -1, 0
	s_and_b64 s[56:57], s[22:23], s[28:29]
	v_cmp_ne_u32_e64 s[22:23], 0, v17
	s_cmp_lg_u64 s[22:23], 0
	s_cselect_b64 s[28:29], -1, 0
	s_cmp_le_i32 s20, s81
	s_cselect_b64 s[94:95], -1, 0
	s_and_b64 s[28:29], s[28:29], s[94:95]
	s_or_b64 s[94:95], s[56:57], s[28:29]
	s_cmp_eq_u32 s2, s61
	s_cbranch_scc1 .Lnsa_sel_noskip
	s_andn2_b64 vcc, exec, s[94:95]
	s_cbranch_vccnz .LBB0_345
	s_mov_b64 s[98:99], s[24:25]
	s_mov_b64 s[100:101], s[22:23]
	s_branch .Lsel_fast

; __device__ __forceinline__ void nsa_wg_task(bf16_t* zb, const bf16_t* kcb, const bf16_t* vctb, const bf16_t* vst, const bf16_t* vwt, int g, int T0, float* accb, LAS unsigned char* lds, int wave, int lane, int tid) {
;     ...
;             const int kb0 = (ws0 + i - (2 * nc + cur + 1)) * 64;
;             bool need[2];
; #pragma unroll
;             for (int r = 0; r < 2; ++r) need[r] = kb0 <= tmax[r] && kb0 + 63 + 512 > t0[r];
;             if (need[0] || need[1]) { nsa_loadk(kbuf, offk0, offk1, ka, kb);
; #pragma unroll
;                 for (int r = 0; r < 2; ++r) if (need[r]) { nsa_scores(ka, kb, q0[r], q1[r], S);
;                     if (kb0 + 512 > tmax[r] && kb0 + 63 <= t0[r]) tile_softmax<0>(S, true, 0, 0, 0u, l[r]);
;                     else tile_softmax<2>(S, false, kb0 + 4 * fq, t[r] - 511, 511u, l[r]);
;                     nsa_pack(S, pf[r]); }
;                 nsa_loadv(vbuf, offv00, offv01, offv10, offv11, vf);
; #pragma unroll
;                 for (int r = 0; r < 2; ++r) if (need[r]) nsa_pv(vf, pf[r], O[r]); }
.LBB0_240:
	s_and_b64 vcc, exec, s[20:21]
	s_cbranch_vccz .LBB0_259
	s_add_i32 s2, s44, s43
	s_lshl_b32 s20, s2, 6
	s_add_i32 s2, s20, 0x23f
	s_cmp_le_i32 s20, s85
	s_cselect_b64 s[22:23], -1, 0
	s_cmp_gt_i32 s2, s88
	s_cselect_b64 s[24:25], -1, 0
	s_and_b64 s[22:23], s[22:23], s[24:25]
	s_cmp_le_i32 s20, s81
	s_cselect_b64 s[24:25], -1, 0
	s_cmp_gt_i32 s2, s89
	s_cselect_b64 s[28:29], -1, 0
	s_and_b64 s[24:25], s[24:25], s[28:29]
	s_or_b64 s[28:29], s[22:23], s[24:25]
	s_cmp_eq_u64 s[28:29], 0
	s_cbranch_scc1 .Lwin_slow
	s_add_i32 s94, s20, 0x200
	s_add_i32 s95, s20, 63
	s_cmp_eq_u64 s[22:23], 0
	s_cbranch_scc1 .Lwin_c1
	s_cmp_le_i32 s94, s85
	s_cbranch_scc1 .Lwin_slow
	s_cmp_gt_i32 s95, s88
	s_cbranch_scc1 .Lwin_slow
.Lwin_c1:
	s_cmp_eq_u64 s[24:25], 0
	s_cbranch_scc1 .Lwin_go
	s_cmp_le_i32 s94, s81
	s_cbranch_scc1 .Lwin_slow
	s_cmp_gt_i32 s95, s89
	s_cbranch_scc1 .Lwin_slow
.Lwin_go:
	s_mov_b64 s[56:57], s[22:23]
	s_mov_b64 s[28:29], s[24:25]
	s_mov_b64 s[98:99], -1
	s_mov_b64 s[100:101], -1
	s_branch .Lsel_fast
.Lwin_slow:
	s_waitcnt lgkmcnt(0)
	v_mov_b64_e32 v[30:31], v[14:15]
	v_mov_b64_e32 v[32:33], v[84:85]
	v_mov_b64_e32 v[36:37], v[88:89]
	v_mov_b64_e32 v[40:41], v[92:93]
	v_mov_b64_e32 v[44:45], v[96:97]
	v_mov_b64_e32 v[48:49], v[100:101]
	v_mov_b64_e32 v[52:53], v[104:105]
	v_mov_b64_e32 v[118:119], v[110:111]
	v_mov_b64_e32 v[122:123], v[114:115]
	s_andn2_b64 vcc, exec, s[28:29]
	v_mov_b64_e32 v[186:187], v[172:173]
	v_mov_b64_e32 v[28:29], v[12:13]
	v_mov_b64_e32 v[26:27], v[10:11]
	v_mov_b64_e32 v[24:25], v[8:9]
	v_mov_b64_e32 v[22:23], v[6:7]
	v_mov_b64_e32 v[20:21], v[4:5]
	v_mov_b64_e32 v[18:19], v[2:3]
	v_mov_b64_e32 v[16:17], v[0:1]
	v_mov_b64_e32 v[34:35], v[86:87]
	v_mov_b64_e32 v[38:39], v[90:91]
	v_mov_b64_e32 v[42:43], v[94:95]
	v_mov_b64_e32 v[46:47], v[98:99]
	v_mov_b64_e32 v[50:51], v[102:103]
	v_mov_b64_e32 v[54:55], v[106:107]
	v_mov_b64_e32 v[116:117], v[108:109]
	v_mov_b64_e32 v[120:121], v[112:113]
	s_cbranch_vccnz .LBB0_259
	v_add_u32_e32 v16, s45, v195
	v_add_u32_e32 v17, s45, v196
	ds_read_b128 v[136:139], v16
	ds_read_b128 v[132:135], v16 offset:2048
	ds_read_b128 v[124:127], v17
	ds_read_b128 v[116:119], v17 offset:2048
	ds_read_b128 v[128:131], v16 offset:4096
	ds_read_b128 v[50:53], v16 offset:6144
	ds_read_b128 v[120:123], v17 offset:4096
	ds_read_b128 v[46:49], v17 offset:6144
	v_cndmask_b32_e64 v16, 0, 1, s[22:23]
	s_add_i32 s28, s20, 0x200
	s_or_b32 s2, s20, 63
	v_add_u32_e32 v54, s20, v208
	v_cmp_ne_u32_e64 s[20:21], 1, v16
	v_mov_b64_e32 v[30:31], v[14:15]
	s_andn2_b64 vcc, exec, s[22:23]
	v_mov_b64_e32 v[28:29], v[12:13]
	v_mov_b64_e32 v[26:27], v[10:11]
	v_mov_b64_e32 v[24:25], v[8:9]
	v_mov_b64_e32 v[22:23], v[6:7]
	v_mov_b64_e32 v[20:21], v[4:5]
	v_mov_b64_e32 v[18:19], v[2:3]
	v_mov_b64_e32 v[16:17], v[0:1]
	v_mov_b32_e32 v186, v172
	s_cbranch_vccnz .LBB0_248
	s_waitcnt lgkmcnt(0)
	v_mfma_f32_16x16x32_bf16 v[16:19], v[136:139], v[60:63], 0
	s_cmp_le_i32 s28, s85
	s_cselect_b64 s[22:23], -1, 0
	s_cmp_gt_i32 s2, s88
	v_mfma_f32_16x16x32_bf16 v[20:23], v[132:135], v[60:63], 0
	s_cselect_b64 s[56:57], -1, 0
	s_or_b64 s[56:57], s[22:23], s[56:57]
	s_mov_b64 s[22:23], -1
	v_mfma_f32_16x16x32_bf16 v[24:27], v[128:131], v[60:63], 0
	s_and_b64 vcc, exec, s[56:57]
	v_mfma_f32_16x16x32_bf16 v[16:19], v[124:127], v[72:75], v[16:19]
	v_mfma_f32_16x16x32_bf16 v[20:23], v[116:119], v[72:75], v[20:23]
	s_nop 6
	v_exp_f32_e32 v44, v18
	v_exp_f32_e32 v45, v19
	v_exp_f32_e32 v40, v20
	v_exp_f32_e32 v39, v21
	v_mfma_f32_16x16x32_bf16 v[18:21], v[120:123], v[72:75], v[24:27]
	v_exp_f32_e32 v42, v22
	v_exp_f32_e32 v41, v23
	v_exp_f32_e32 v16, v16
	v_mfma_f32_16x16x32_bf16 v[22:25], v[50:53], v[60:63], 0
	v_exp_f32_e32 v17, v17
	s_nop 2
	v_exp_f32_e32 v34, v18
	v_exp_f32_e32 v35, v19
	v_exp_f32_e32 v36, v20
	v_exp_f32_e32 v33, v21
	v_mfma_f32_16x16x32_bf16 v[18:21], v[46:49], v[72:75], v[22:25]
	s_nop 7
	v_exp_f32_e32 v32, v18
	v_exp_f32_e32 v43, v19
	v_exp_f32_e32 v38, v20
	v_exp_f32_e32 v37, v21
	s_cbranch_vccnz .LBB0_245
	v_add_f32_e32 v18, 0, v16
	v_add_f32_e32 v18, v17, v18
	v_add_f32_e32 v18, v44, v18
	v_add_f32_e32 v18, v45, v18
	v_add_f32_e32 v18, v40, v18
	v_add_f32_e32 v18, v39, v18
	v_add_f32_e32 v18, v42, v18
	v_add_f32_e32 v18, v41, v18
	v_add_f32_e32 v18, v34, v18
	v_add_f32_e32 v18, v35, v18
	v_add_f32_e32 v18, v36, v18
	v_add_f32_e32 v18, v33, v18
	v_add_f32_e32 v18, v32, v18
	v_add_f32_e32 v18, v43, v18
	v_add_f32_e32 v18, v38, v18
	v_add_f32_e32 v55, v37, v18
	s_mov_b64 s[22:23], 0
